# GEMM K-loops: MFMA-phase priority dropped three MFMA groups (12 MFMAs) before the phase ends
# baseline (speedup 1.0000x reference)
.LBB0_677:
	s_add_i32 s10, s10, 64
	s_waitcnt lgkmcnt(2)
	v_mfma_f32_16x16x32_bf16 v[162:165], v[202:205], v[178:181], v[162:165]
	v_mfma_f32_16x16x32_bf16 v[154:157], v[202:205], v[182:185], v[154:157]
	v_mfma_f32_16x16x32_bf16 v[134:137], v[202:205], v[186:189], v[134:137]
	v_mfma_f32_16x16x32_bf16 v[114:117], v[202:205], v[190:193], v[114:117]
	ds_read_b128 v[202:205], v216 offset:8192
	s_waitcnt lgkmcnt(2)
	v_mfma_f32_16x16x32_bf16 v[82:85], v[198:201], v[190:193], v[82:85]
	v_mfma_f32_16x16x32_bf16 v[86:89], v[198:201], v[186:189], v[86:89]
	v_mfma_f32_16x16x32_bf16 v[90:93], v[198:201], v[182:185], v[90:93]
	v_mfma_f32_16x16x32_bf16 v[94:97], v[198:201], v[178:181], v[94:97]
	ds_read_b128 v[198:201], v216 offset:10240
	s_waitcnt lgkmcnt(2)
	v_mfma_f32_16x16x32_bf16 v[78:81], v[194:197], v[178:181], v[78:81]
	v_mfma_f32_16x16x32_bf16 v[74:77], v[194:197], v[182:185], v[74:77]
	v_mfma_f32_16x16x32_bf16 v[70:73], v[194:197], v[186:189], v[70:73]
	v_mfma_f32_16x16x32_bf16 v[66:69], v[194:197], v[190:193], v[66:69]
	ds_read_b128 v[194:197], v216 offset:12288
	s_waitcnt lgkmcnt(2)
	v_mfma_f32_16x16x32_bf16 v[50:53], v[202:205], v[190:193], v[50:53]
	v_mfma_f32_16x16x32_bf16 v[54:57], v[202:205], v[186:189], v[54:57]
	v_mfma_f32_16x16x32_bf16 v[58:61], v[202:205], v[182:185], v[58:61]
	v_mfma_f32_16x16x32_bf16 v[62:65], v[202:205], v[178:181], v[62:65]
	ds_read_b128 v[202:205], v216 offset:14336
	s_setprio 0
	s_waitcnt lgkmcnt(2)
	v_mfma_f32_16x16x32_bf16 v[46:49], v[198:201], v[178:181], v[46:49]
	v_mfma_f32_16x16x32_bf16 v[42:45], v[198:201], v[182:185], v[42:45]
	v_mfma_f32_16x16x32_bf16 v[38:41], v[198:201], v[186:189], v[38:41]
	v_mfma_f32_16x16x32_bf16 v[34:37], v[198:201], v[190:193], v[34:37]
	s_waitcnt lgkmcnt(1)
	v_mfma_f32_16x16x32_bf16 v[6:9], v[194:197], v[190:193], v[6:9]
	v_mfma_f32_16x16x32_bf16 v[18:21], v[194:197], v[186:189], v[18:21]
	v_mfma_f32_16x16x32_bf16 v[26:29], v[194:197], v[182:185], v[26:29]
	v_mfma_f32_16x16x32_bf16 v[30:33], v[194:197], v[178:181], v[30:33]
	s_waitcnt lgkmcnt(0)
	v_mfma_f32_16x16x32_bf16 v[22:25], v[202:205], v[178:181], v[22:25]
	v_mfma_f32_16x16x32_bf16 v[14:17], v[202:205], v[182:185], v[14:17]
	v_mfma_f32_16x16x32_bf16 v[10:13], v[202:205], v[186:189], v[10:13]
	v_mfma_f32_16x16x32_bf16 v[2:5], v[202:205], v[190:193], v[2:5]
	s_add_u32 s38, s38, 0x80
	s_addc_u32 s39, s39, 0
	s_add_u32 s40, s40, 0x80
	s_addc_u32 s41, s41, 0
	s_and_b64 vcc, exec, s[52:53]
	s_cbranch_vccnz .LBB0_684

.LBB0_1483:
	s_add_i32 s1, s1, 64
	s_waitcnt lgkmcnt(2)
	v_mfma_f32_16x16x32_bf16 v[162:165], v[202:205], v[178:181], v[162:165]
	v_mfma_f32_16x16x32_bf16 v[154:157], v[202:205], v[182:185], v[154:157]
	v_mfma_f32_16x16x32_bf16 v[122:125], v[202:205], v[186:189], v[122:125]
	v_mfma_f32_16x16x32_bf16 v[106:109], v[202:205], v[190:193], v[106:109]
	ds_read_b128 v[202:205], v216 offset:8192
	s_waitcnt lgkmcnt(2)
	v_mfma_f32_16x16x32_bf16 v[82:85], v[198:201], v[190:193], v[82:85]
	v_mfma_f32_16x16x32_bf16 v[86:89], v[198:201], v[186:189], v[86:89]
	v_mfma_f32_16x16x32_bf16 v[90:93], v[198:201], v[182:185], v[90:93]
	v_mfma_f32_16x16x32_bf16 v[94:97], v[198:201], v[178:181], v[94:97]
	ds_read_b128 v[198:201], v216 offset:10240
	s_waitcnt lgkmcnt(2)
	v_mfma_f32_16x16x32_bf16 v[78:81], v[194:197], v[178:181], v[78:81]
	v_mfma_f32_16x16x32_bf16 v[74:77], v[194:197], v[182:185], v[74:77]
	v_mfma_f32_16x16x32_bf16 v[70:73], v[194:197], v[186:189], v[70:73]
	v_mfma_f32_16x16x32_bf16 v[66:69], v[194:197], v[190:193], v[66:69]
	ds_read_b128 v[194:197], v216 offset:12288
	s_waitcnt lgkmcnt(2)
	v_mfma_f32_16x16x32_bf16 v[50:53], v[202:205], v[190:193], v[50:53]
	v_mfma_f32_16x16x32_bf16 v[54:57], v[202:205], v[186:189], v[54:57]
	v_mfma_f32_16x16x32_bf16 v[58:61], v[202:205], v[182:185], v[58:61]
	v_mfma_f32_16x16x32_bf16 v[62:65], v[202:205], v[178:181], v[62:65]
	ds_read_b128 v[202:205], v216 offset:14336
	s_setprio 0
	s_waitcnt lgkmcnt(2)
	v_mfma_f32_16x16x32_bf16 v[46:49], v[198:201], v[178:181], v[46:49]
	v_mfma_f32_16x16x32_bf16 v[42:45], v[198:201], v[182:185], v[42:45]
	v_mfma_f32_16x16x32_bf16 v[38:41], v[198:201], v[186:189], v[38:41]
	v_mfma_f32_16x16x32_bf16 v[34:37], v[198:201], v[190:193], v[34:37]
	s_waitcnt lgkmcnt(1)
	v_mfma_f32_16x16x32_bf16 v[6:9], v[194:197], v[190:193], v[6:9]
	v_mfma_f32_16x16x32_bf16 v[18:21], v[194:197], v[186:189], v[18:21]
	v_mfma_f32_16x16x32_bf16 v[26:29], v[194:197], v[182:185], v[26:29]
	v_mfma_f32_16x16x32_bf16 v[30:33], v[194:197], v[178:181], v[30:33]
	s_waitcnt lgkmcnt(0)
	v_mfma_f32_16x16x32_bf16 v[22:25], v[202:205], v[178:181], v[22:25]
	v_mfma_f32_16x16x32_bf16 v[14:17], v[202:205], v[182:185], v[14:17]
	v_mfma_f32_16x16x32_bf16 v[10:13], v[202:205], v[186:189], v[10:13]
	v_mfma_f32_16x16x32_bf16 v[2:5], v[202:205], v[190:193], v[2:5]
	s_add_u32 s38, s38, 0x80
	s_addc_u32 s39, s39, 0
	s_add_u32 s40, s40, 0x80
	s_addc_u32 s41, s41, 0
	s_and_b64 vcc, exec, s[44:45]
	s_cbranch_vccnz .LBB0_1490

.LBB0_1681:
	s_waitcnt lgkmcnt(2)
	v_mfma_f32_16x16x32_bf16 v[162:165], v[202:205], v[178:181], v[162:165]
	v_mfma_f32_16x16x32_bf16 v[166:169], v[202:205], v[182:185], v[166:169]
	v_mfma_f32_16x16x32_bf16 v[170:173], v[202:205], v[186:189], v[170:173]
	v_mfma_f32_16x16x32_bf16 v[174:177], v[202:205], v[190:193], v[174:177]
	ds_read_b128 v[202:205], v217 offset:8192
	s_waitcnt lgkmcnt(2)
	v_mfma_f32_16x16x32_bf16 v[158:161], v[198:201], v[190:193], v[158:161]
	v_mfma_f32_16x16x32_bf16 v[154:157], v[198:201], v[186:189], v[154:157]
	v_mfma_f32_16x16x32_bf16 v[150:153], v[198:201], v[182:185], v[150:153]
	v_mfma_f32_16x16x32_bf16 v[146:149], v[198:201], v[178:181], v[146:149]
	ds_read_b128 v[198:201], v217 offset:10240
	s_waitcnt lgkmcnt(2)
	v_mfma_f32_16x16x32_bf16 v[118:121], v[194:197], v[178:181], v[118:121]
	v_mfma_f32_16x16x32_bf16 v[122:125], v[194:197], v[182:185], v[122:125]
	v_mfma_f32_16x16x32_bf16 v[126:129], v[194:197], v[186:189], v[126:129]
	v_mfma_f32_16x16x32_bf16 v[130:133], v[194:197], v[190:193], v[130:133]
	ds_read_b128 v[194:197], v217 offset:12288
	s_waitcnt lgkmcnt(2)
	v_mfma_f32_16x16x32_bf16 v[110:113], v[202:205], v[190:193], v[110:113]
	v_mfma_f32_16x16x32_bf16 v[106:109], v[202:205], v[186:189], v[106:109]
	v_mfma_f32_16x16x32_bf16 v[102:105], v[202:205], v[182:185], v[102:105]
	v_mfma_f32_16x16x32_bf16 v[98:101], v[202:205], v[178:181], v[98:101]
	ds_read_b128 v[202:205], v217 offset:14336
	s_setprio 0
	s_waitcnt lgkmcnt(2)
	v_mfma_f32_16x16x32_bf16 v[82:85], v[198:201], v[178:181], v[82:85]
	v_mfma_f32_16x16x32_bf16 v[86:89], v[198:201], v[182:185], v[86:89]
	v_mfma_f32_16x16x32_bf16 v[90:93], v[198:201], v[186:189], v[90:93]
	v_mfma_f32_16x16x32_bf16 v[94:97], v[198:201], v[190:193], v[94:97]
	s_waitcnt lgkmcnt(1)
	v_mfma_f32_16x16x32_bf16 v[78:81], v[194:197], v[190:193], v[78:81]
	v_mfma_f32_16x16x32_bf16 v[74:77], v[194:197], v[186:189], v[74:77]
	v_mfma_f32_16x16x32_bf16 v[70:73], v[194:197], v[182:185], v[70:73]
	v_mfma_f32_16x16x32_bf16 v[66:69], v[194:197], v[178:181], v[66:69]
	s_waitcnt lgkmcnt(0)
	v_mfma_f32_16x16x32_bf16 v[50:53], v[202:205], v[178:181], v[50:53]
	v_mfma_f32_16x16x32_bf16 v[54:57], v[202:205], v[182:185], v[54:57]
	v_mfma_f32_16x16x32_bf16 v[58:61], v[202:205], v[186:189], v[58:61]
	v_mfma_f32_16x16x32_bf16 v[62:65], v[202:205], v[190:193], v[62:65]
	s_add_u32 s36, s36, 0x80
	s_addc_u32 s37, s37, 0
	s_add_u32 s38, s38, 0x80
	s_addc_u32 s39, s39, 0
	s_cmpk_gt_u32 s1, 0x3bf
	s_cbranch_scc1 .LBB0_1686

.LBB0_1814:
	s_add_i32 s20, s20, 64
	s_waitcnt lgkmcnt(2)
	v_mfma_f32_16x16x32_bf16 v[162:165], v[202:205], v[178:181], v[162:165]
	v_mfma_f32_16x16x32_bf16 v[154:157], v[202:205], v[182:185], v[154:157]
	v_mfma_f32_16x16x32_bf16 v[118:121], v[202:205], v[186:189], v[118:121]
	v_mfma_f32_16x16x32_bf16 v[106:109], v[202:205], v[190:193], v[106:109]
	ds_read_b128 v[202:205], v216 offset:8192
	s_waitcnt lgkmcnt(2)
	v_mfma_f32_16x16x32_bf16 v[82:85], v[198:201], v[190:193], v[82:85]
	v_mfma_f32_16x16x32_bf16 v[86:89], v[198:201], v[186:189], v[86:89]
	v_mfma_f32_16x16x32_bf16 v[90:93], v[198:201], v[182:185], v[90:93]
	v_mfma_f32_16x16x32_bf16 v[94:97], v[198:201], v[178:181], v[94:97]
	ds_read_b128 v[198:201], v216 offset:10240
	s_waitcnt lgkmcnt(2)
	v_mfma_f32_16x16x32_bf16 v[78:81], v[194:197], v[178:181], v[78:81]
	v_mfma_f32_16x16x32_bf16 v[74:77], v[194:197], v[182:185], v[74:77]
	v_mfma_f32_16x16x32_bf16 v[70:73], v[194:197], v[186:189], v[70:73]
	v_mfma_f32_16x16x32_bf16 v[66:69], v[194:197], v[190:193], v[66:69]
	ds_read_b128 v[194:197], v216 offset:12288
	s_waitcnt lgkmcnt(2)
	v_mfma_f32_16x16x32_bf16 v[50:53], v[202:205], v[190:193], v[50:53]
	v_mfma_f32_16x16x32_bf16 v[54:57], v[202:205], v[186:189], v[54:57]
	v_mfma_f32_16x16x32_bf16 v[58:61], v[202:205], v[182:185], v[58:61]
	v_mfma_f32_16x16x32_bf16 v[62:65], v[202:205], v[178:181], v[62:65]
	ds_read_b128 v[202:205], v216 offset:14336
	s_setprio 0
	s_waitcnt lgkmcnt(2)
	v_mfma_f32_16x16x32_bf16 v[46:49], v[198:201], v[178:181], v[46:49]
	v_mfma_f32_16x16x32_bf16 v[42:45], v[198:201], v[182:185], v[42:45]
	v_mfma_f32_16x16x32_bf16 v[38:41], v[198:201], v[186:189], v[38:41]
	v_mfma_f32_16x16x32_bf16 v[34:37], v[198:201], v[190:193], v[34:37]
	s_waitcnt lgkmcnt(1)
	v_mfma_f32_16x16x32_bf16 v[6:9], v[194:197], v[190:193], v[6:9]
	v_mfma_f32_16x16x32_bf16 v[18:21], v[194:197], v[186:189], v[18:21]
	v_mfma_f32_16x16x32_bf16 v[26:29], v[194:197], v[182:185], v[26:29]
	v_mfma_f32_16x16x32_bf16 v[30:33], v[194:197], v[178:181], v[30:33]
	s_waitcnt lgkmcnt(0)
	v_mfma_f32_16x16x32_bf16 v[22:25], v[202:205], v[178:181], v[22:25]
	v_mfma_f32_16x16x32_bf16 v[14:17], v[202:205], v[182:185], v[14:17]
	v_mfma_f32_16x16x32_bf16 v[10:13], v[202:205], v[186:189], v[10:13]
	v_mfma_f32_16x16x32_bf16 v[2:5], v[202:205], v[190:193], v[2:5]
	s_add_u32 s36, s36, 0x80
	s_addc_u32 s37, s37, 0
	s_add_u32 s38, s38, 0x80
	s_addc_u32 s39, s39, 0
	s_and_b64 vcc, exec, s[40:41]
	s_cbranch_vccnz .LBB0_1821
